# v012 + P0 Fourier-weight DFT fold on the f32 matrix cores (v_mfma_f32_16x16x4_f32, same fma order) instead of the f32 VALU/LDS-lookup loop
# speedup vs baseline: 1.0008x; 1.0008x over previous
; __global__ void __launch_bounds__(512, 2) fwd_megakernel(Args a) {
;     ...
;             for (int item = c; item < 128; item += G) {
;                 const int kc = item >> 2, g = item & 3, k0 = kc * 64;
;                 if (tid < 128) tab[tid] = cosf((float)tid * (6.283185307179586f / 128.f));
;                 for (int i = 0; i < 16; ++i) { const int idx = tid + 512 * i, kk = idx >> 7, cc = idx & 127;
;                     Wt[kk * 129 + cc] = a.w_in[(size_t)(k0 + kk) * 5120 + 4608 + g * 128 + cc] * a.n1g[k0 + kk]; }
.LBB0_53:
	s_and_saveexec_b64 s[2:3], s[0:1]
	ds_write_b32 v3, v17 offset:33024
	s_or_b64 exec, exec, s[2:3]
	s_lshl_b32 s2, s7, 4
	s_andn2_b32 s2, s2, 63
	s_lshl_b32 s3, s7, 7
	s_and_b32 s33, s3, 0x180
	v_add_u32_e32 v8, s2, v18
	s_waitcnt lgkmcnt(0)
	v_mov_b64_e32 v[10:11], s[42:43]
	v_mad_i64_i32 v[12:13], s[14:15], v8, s4, v[10:11]
	s_lshl_b32 s12, s33, 2
	v_lshl_add_u64 v[12:13], v[12:13], 0, s[12:13]
	v_add_u32_e32 v58, s2, v19
	v_lshl_add_u64 v[12:13], v[12:13], 0, v[4:5]
	v_mad_i64_i32 v[60:61], s[14:15], v58, s4, v[10:11]
	v_add_co_u32_e32 v12, vcc, 0x4000, v12
	v_lshl_add_u64 v[60:61], v[60:61], 0, s[12:13]
	v_add_u32_e32 v62, s2, v20
	v_addc_co_u32_e32 v13, vcc, 0, v13, vcc
	v_lshl_add_u64 v[60:61], v[60:61], 0, v[4:5]
	v_mad_i64_i32 v[64:65], s[14:15], v62, s4, v[10:11]
	v_add_co_u32_e32 v60, vcc, s5, v60
	v_lshl_add_u64 v[64:65], v[64:65], 0, s[12:13]
	v_add_u32_e32 v66, s2, v21
	v_addc_co_u32_e32 v61, vcc, 0, v61, vcc
	v_lshl_add_u64 v[64:65], v[64:65], 0, v[4:5]
	v_mad_i64_i32 v[68:69], s[14:15], v66, s4, v[10:11]
	v_add_co_u32_e32 v64, vcc, s5, v64
	v_lshl_add_u64 v[68:69], v[68:69], 0, s[12:13]
	v_add_u32_e32 v70, s2, v22
	v_addc_co_u32_e32 v65, vcc, 0, v65, vcc
	v_lshl_add_u64 v[68:69], v[68:69], 0, v[4:5]
	v_mad_i64_i32 v[72:73], s[14:15], v70, s4, v[10:11]
	v_add_co_u32_e32 v68, vcc, s5, v68
	v_lshl_add_u64 v[72:73], v[72:73], 0, s[12:13]
	v_add_u32_e32 v74, s2, v23
	v_addc_co_u32_e32 v69, vcc, 0, v69, vcc
	v_lshl_add_u64 v[72:73], v[72:73], 0, v[4:5]
	v_mad_i64_i32 v[76:77], s[14:15], v74, s4, v[10:11]
	v_add_co_u32_e32 v72, vcc, s5, v72
	v_lshl_add_u64 v[76:77], v[76:77], 0, s[12:13]
	v_add_u32_e32 v78, s2, v24
	v_addc_co_u32_e32 v73, vcc, 0, v73, vcc
	v_lshl_add_u64 v[76:77], v[76:77], 0, v[4:5]
	v_mad_i64_i32 v[80:81], s[14:15], v78, s4, v[10:11]
	v_add_co_u32_e32 v76, vcc, s5, v76
	v_lshl_add_u64 v[80:81], v[80:81], 0, s[12:13]
	v_add_u32_e32 v82, s2, v25
	v_addc_co_u32_e32 v77, vcc, 0, v77, vcc
	v_lshl_add_u64 v[80:81], v[80:81], 0, v[4:5]
	v_mad_i64_i32 v[84:85], s[14:15], v82, s4, v[10:11]
	v_add_co_u32_e32 v80, vcc, s5, v80
	v_lshl_add_u64 v[84:85], v[84:85], 0, s[12:13]
	v_add_u32_e32 v86, s2, v26
	v_addc_co_u32_e32 v81, vcc, 0, v81, vcc
	v_lshl_add_u64 v[84:85], v[84:85], 0, v[4:5]
	v_mad_i64_i32 v[88:89], s[14:15], v86, s4, v[10:11]
	v_add_co_u32_e32 v84, vcc, s5, v84
	v_lshl_add_u64 v[88:89], v[88:89], 0, s[12:13]
	v_add_u32_e32 v90, s2, v27
	v_addc_co_u32_e32 v85, vcc, 0, v85, vcc
	v_lshl_add_u64 v[88:89], v[88:89], 0, v[4:5]
	v_mad_i64_i32 v[92:93], s[14:15], v90, s4, v[10:11]
	v_ashrrev_i32_e32 v9, 31, v8
	v_add_co_u32_e32 v88, vcc, s5, v88
	v_lshl_add_u64 v[92:93], v[92:93], 0, s[12:13]
	v_add_u32_e32 v94, s2, v28
	v_lshl_add_u64 v[8:9], v[8:9], 2, s[40:41]
	v_ashrrev_i32_e32 v59, 31, v58
	v_addc_co_u32_e32 v89, vcc, 0, v89, vcc
	v_lshl_add_u64 v[92:93], v[92:93], 0, v[4:5]
	v_mad_i64_i32 v[96:97], s[14:15], v94, s4, v[10:11]
	global_load_dword v12, v[12:13], off offset:2048
	s_nop 0
	global_load_dword v13, v[8:9], off
	global_load_dword v57, v[60:61], off offset:2048
	v_lshl_add_u64 v[8:9], v[58:59], 2, s[40:41]
	v_ashrrev_i32_e32 v63, 31, v62
	v_add_co_u32_e32 v92, vcc, s5, v92
	v_lshl_add_u64 v[96:97], v[96:97], 0, s[12:13]
	v_add_u32_e32 v98, s2, v29
	global_load_dword v58, v[8:9], off
	global_load_dword v59, v[64:65], off offset:2048
	v_lshl_add_u64 v[8:9], v[62:63], 2, s[40:41]
	v_ashrrev_i32_e32 v67, 31, v66
	v_addc_co_u32_e32 v93, vcc, 0, v93, vcc
	v_lshl_add_u64 v[96:97], v[96:97], 0, v[4:5]
	v_mad_i64_i32 v[100:101], s[14:15], v98, s4, v[10:11]
	global_load_dword v60, v[8:9], off
	global_load_dword v61, v[68:69], off offset:2048
	v_lshl_add_u64 v[8:9], v[66:67], 2, s[40:41]
	v_ashrrev_i32_e32 v71, 31, v70
	v_add_co_u32_e32 v96, vcc, s5, v96
	v_lshl_add_u64 v[100:101], v[100:101], 0, s[12:13]
	v_add_u32_e32 v102, s2, v30
	global_load_dword v62, v[8:9], off
	global_load_dword v63, v[72:73], off offset:2048
	v_lshl_add_u64 v[8:9], v[70:71], 2, s[40:41]
	v_ashrrev_i32_e32 v75, 31, v74
	v_addc_co_u32_e32 v97, vcc, 0, v97, vcc
	v_lshl_add_u64 v[100:101], v[100:101], 0, v[4:5]
	v_mad_i64_i32 v[104:105], s[14:15], v102, s4, v[10:11]
	global_load_dword v64, v[8:9], off
	global_load_dword v65, v[76:77], off offset:2048
	v_lshl_add_u64 v[8:9], v[74:75], 2, s[40:41]
	v_ashrrev_i32_e32 v79, 31, v78
	v_add_co_u32_e32 v100, vcc, s5, v100
	v_lshl_add_u64 v[104:105], v[104:105], 0, s[12:13]
	v_add_u32_e32 v106, s2, v31
	global_load_dword v66, v[8:9], off
	global_load_dword v67, v[80:81], off offset:2048
	v_lshl_add_u64 v[8:9], v[78:79], 2, s[40:41]
	v_ashrrev_i32_e32 v83, 31, v82
	v_addc_co_u32_e32 v101, vcc, 0, v101, vcc
	v_lshl_add_u64 v[104:105], v[104:105], 0, v[4:5]
	v_mad_i64_i32 v[108:109], s[14:15], v106, s4, v[10:11]
	global_load_dword v68, v[8:9], off
	global_load_dword v69, v[84:85], off offset:2048
	v_lshl_add_u64 v[8:9], v[82:83], 2, s[40:41]
	v_ashrrev_i32_e32 v87, 31, v86
	v_add_co_u32_e32 v104, vcc, s5, v104
	v_lshl_add_u64 v[108:109], v[108:109], 0, s[12:13]
	v_add_u32_e32 v110, s2, v32
	global_load_dword v70, v[8:9], off
	global_load_dword v71, v[88:89], off offset:2048
	v_lshl_add_u64 v[8:9], v[86:87], 2, s[40:41]
	v_ashrrev_i32_e32 v91, 31, v90
	v_addc_co_u32_e32 v105, vcc, 0, v105, vcc
	v_lshl_add_u64 v[108:109], v[108:109], 0, v[4:5]
	v_mad_i64_i32 v[112:113], s[14:15], v110, s4, v[10:11]
	global_load_dword v72, v[8:9], off
	global_load_dword v73, v[92:93], off offset:2048
	v_lshl_add_u64 v[8:9], v[90:91], 2, s[40:41]
	v_ashrrev_i32_e32 v95, 31, v94
	v_add_co_u32_e32 v108, vcc, s5, v108
	v_lshl_add_u64 v[112:113], v[112:113], 0, s[12:13]
	v_add_u32_e32 v114, s2, v33
; __global__ void __launch_bounds__(512, 2) fwd_megakernel(Args a) {
;     ...
;                 for (int i = 0; i < 16; ++i) { const int idx = tid + 512 * i, kk = idx >> 7, cc = idx & 127;
;                     Wt[kk * 129 + cc] = a.w_in[(size_t)(k0 + kk) * 5120 + 4608 + g * 128 + cc] * a.n1g[k0 + kk]; }
;                 __syncthreads();
;                 const int kk = tid & 63, jw = tid >> 6;
;                 for (int jj = 0; jj < 16; ++jj) {
;                     const int j = jw + 8 * jj; float ac = 0.f, as = 0.f;
;                     for (int cc = 0; cc < 128; ++cc) { const float w = Wt[kk * 129 + cc]; const int idx = (j * cc) & 127; ac += w * tab[idx]; as += w * tab[(idx - 32) & 127]; }
	global_load_dword v74, v[8:9], off
	global_load_dword v75, v[96:97], off offset:2048
	v_lshl_add_u64 v[8:9], v[94:95], 2, s[40:41]
	v_ashrrev_i32_e32 v99, 31, v98
	v_addc_co_u32_e32 v109, vcc, 0, v109, vcc
	v_lshl_add_u64 v[112:113], v[112:113], 0, v[4:5]
	v_mad_i64_i32 v[10:11], s[14:15], v114, s4, v[10:11]
	global_load_dword v76, v[8:9], off
	global_load_dword v77, v[100:101], off offset:2048
	v_lshl_add_u64 v[8:9], v[98:99], 2, s[40:41]
	v_ashrrev_i32_e32 v103, 31, v102
	v_add_co_u32_e32 v112, vcc, s5, v112
	v_lshl_add_u64 v[10:11], v[10:11], 0, s[12:13]
	global_load_dword v78, v[8:9], off
	global_load_dword v79, v[104:105], off offset:2048
	v_lshl_add_u64 v[8:9], v[102:103], 2, s[40:41]
	v_ashrrev_i32_e32 v107, 31, v106
	v_addc_co_u32_e32 v113, vcc, 0, v113, vcc
	v_lshl_add_u64 v[10:11], v[10:11], 0, v[4:5]
	global_load_dword v80, v[8:9], off
	global_load_dword v81, v[108:109], off offset:2048
	v_lshl_add_u64 v[8:9], v[106:107], 2, s[40:41]
	v_ashrrev_i32_e32 v111, 31, v110
	v_add_co_u32_e32 v10, vcc, s5, v10
	global_load_dword v82, v[8:9], off
	global_load_dword v83, v[112:113], off offset:2048
	v_lshl_add_u64 v[8:9], v[110:111], 2, s[40:41]
	v_ashrrev_i32_e32 v115, 31, v114
	v_addc_co_u32_e32 v11, vcc, 0, v11, vcc
	global_load_dword v84, v[8:9], off
	s_nop 0
	global_load_dword v10, v[10:11], off offset:2048
	v_lshl_add_u64 v[8:9], v[114:115], 2, s[40:41]
	global_load_dword v8, v[8:9], off
	s_waitcnt vmcnt(30)
	v_mul_f32_e32 v9, v12, v13
	ds_write_b32 v41, v9
	s_waitcnt vmcnt(28)
	v_mul_f32_e32 v9, v57, v58
	ds_write_b32 v42, v9
	s_waitcnt vmcnt(26)
	v_mul_f32_e32 v9, v59, v60
	ds_write_b32 v43, v9
	s_waitcnt vmcnt(24)
	v_mul_f32_e32 v9, v61, v62
	ds_write_b32 v44, v9
	s_ashr_i32 s3, s2, 31
	s_waitcnt vmcnt(22)
	v_mul_f32_e32 v9, v63, v64
	ds_write_b32 v45, v9
	s_mov_b32 s12, 0
	v_mov_b32_e32 v12, v40
	v_mov_b32_e32 v13, v39
	v_mov_b32_e32 v57, v38
	v_mov_b32_e32 v58, v37
	s_waitcnt vmcnt(20)
	v_mul_f32_e32 v9, v65, v66
	ds_write_b32 v46, v9
	v_mov_b32_e32 v59, v36
	v_mov_b32_e32 v60, v35
	v_mov_b32_e32 v61, v34
	v_mov_b32_e32 v62, v1
	s_waitcnt vmcnt(18)
	v_mul_f32_e32 v9, v67, v68
	ds_write_b32 v47, v9
	s_waitcnt vmcnt(16)
	v_mul_f32_e32 v9, v69, v70
	ds_write_b32 v48, v9
	s_waitcnt vmcnt(14)
	v_mul_f32_e32 v9, v71, v72
	ds_write_b32 v49, v9
	s_waitcnt vmcnt(12)
	v_mul_f32_e32 v9, v73, v74
	ds_write_b32 v50, v9
	s_waitcnt vmcnt(10)
	v_mul_f32_e32 v9, v75, v76
	ds_write_b32 v51, v9
	s_waitcnt vmcnt(8)
	v_mul_f32_e32 v9, v77, v78
	ds_write_b32 v52, v9
	s_waitcnt vmcnt(6)
	v_mul_f32_e32 v9, v79, v80
	ds_write_b32 v53, v9
	s_waitcnt vmcnt(4)
	v_mul_f32_e32 v9, v81, v82
	ds_write_b32 v54, v9
	s_waitcnt vmcnt(2)
	v_mul_f32_e32 v9, v83, v84
	ds_write_b32 v55, v9
	s_waitcnt vmcnt(0)
	v_mul_f32_e32 v8, v10, v8
	ds_write_b32 v56, v8
	s_waitcnt lgkmcnt(0)
	s_barrier
	v_and_b32_e32 v57, 15, v14
	v_bfe_u32 v58, v14, 4, 2
	v_readfirstlane_b32 s3, v1
	s_nop 3
	s_lshl_b32 s12, s3, 4
	v_add_u32_e32 v59, s12, v57
	v_mul_u32_u24_e32 v60, v59, v58
	v_lshlrev_b32_e32 v66, 2, v60
	v_and_b32_e32 v66, 0x1ff, v66
	v_add_u32_e32 v67, 0x180, v66
	v_and_b32_e32 v67, 0x1ff, v67
	v_lshlrev_b32_e32 v68, 4, v59
	v_mul_u32_u24_e32 v65, 0x204, v57
	v_lshl_add_u32 v65, v58, 2, v65
	v_mov_b32_e32 v76, 0
	v_mov_b32_e32 v77, 0
	v_mov_b32_e32 v78, 0
	v_mov_b32_e32 v79, 0
	v_mov_b32_e32 v80, 0
	v_mov_b32_e32 v81, 0
	v_mov_b32_e32 v82, 0
	v_mov_b32_e32 v83, 0
	v_mov_b32_e32 v84, 0
	v_mov_b32_e32 v85, 0
	v_mov_b32_e32 v86, 0
	v_mov_b32_e32 v87, 0
	v_mov_b32_e32 v88, 0
	v_mov_b32_e32 v89, 0
	v_mov_b32_e32 v90, 0
	v_mov_b32_e32 v91, 0
	v_mov_b32_e32 v92, 0
	v_mov_b32_e32 v93, 0
	v_mov_b32_e32 v94, 0
	v_mov_b32_e32 v95, 0
	v_mov_b32_e32 v96, 0
	v_mov_b32_e32 v97, 0
	v_mov_b32_e32 v98, 0
	v_mov_b32_e32 v99, 0
	v_mov_b32_e32 v100, 0
	v_mov_b32_e32 v101, 0
	v_mov_b32_e32 v102, 0
	v_mov_b32_e32 v103, 0
	v_mov_b32_e32 v104, 0
	v_mov_b32_e32 v105, 0
	v_mov_b32_e32 v106, 0
	v_mov_b32_e32 v107, 0
	s_mov_b32 s3, 0
; __device__ __forceinline__ unsigned f2bf(float f) { unsigned u = __builtin_bit_cast(unsigned, f); return (u + 0x7fffu + ((u >> 16) & 1u)) >> 16; }
; __global__ void __launch_bounds__(512, 2) fwd_megakernel(Args a) {
;     ...
;                 for (int jj = 0; jj < 16; ++jj) {
;                     const int j = jw + 8 * jj; float ac = 0.f, as = 0.f;
;                     for (int cc = 0; cc < 128; ++cc) { const float w = Wt[kk * 129 + cc]; const int idx = (j * cc) & 127; ac += w * tab[idx]; as += w * tab[(idx - 32) & 127]; }
;                     WFC[(size_t)(g * 128 + j) * DM + k0 + kk] = (bf16_t)f2bf(ac);
;                     WFC[(size_t)(512 + g * 128 + j) * DM + k0 + kk] = (bf16_t)f2bf(-as);
.Lmy_dft_k:
	ds_read_b32 v70, v66 offset:33024
	ds_read_b32 v71, v67 offset:33024
	ds_read_b32 v72, v65
	ds_read_b32 v73, v65 offset:8256
	ds_read_b32 v74, v65 offset:16512
	ds_read_b32 v75, v65 offset:24768
	v_add_u32_e32 v66, v66, v68
	v_and_b32_e32 v66, 0x1ff, v66
	v_add_u32_e32 v67, 0x180, v66
	v_and_b32_e32 v67, 0x1ff, v67
	v_add_u32_e32 v65, 16, v65
	s_add_i32 s3, s3, 1
	s_waitcnt lgkmcnt(0)
	v_mfma_f32_16x16x4_f32 v[76:79], v70, v72, v[76:79]
	v_mfma_f32_16x16x4_f32 v[80:83], v70, v73, v[80:83]
	v_mfma_f32_16x16x4_f32 v[84:87], v70, v74, v[84:87]
	v_mfma_f32_16x16x4_f32 v[88:91], v70, v75, v[88:91]
	v_mfma_f32_16x16x4_f32 v[92:95], v71, v72, v[92:95]
	v_mfma_f32_16x16x4_f32 v[96:99], v71, v73, v[96:99]
	v_mfma_f32_16x16x4_f32 v[100:103], v71, v74, v[100:103]
	v_mfma_f32_16x16x4_f32 v[104:107], v71, v75, v[104:107]
	s_cmp_lt_u32 s3, 32
	s_cbranch_scc1 .Lmy_dft_k
	s_nop 7
	s_nop 7
	v_lshl_add_u32 v60, v58, 2, s12
	v_add_u32_e32 v60, s33, v60
	v_lshlrev_b32_e32 v60, 12, v60
	v_add_u32_e32 v61, s2, v57
	v_lshl_add_u32 v60, v61, 1, v60
	v_add_u32_e32 v61, 0x1000, v60
	v_add_u32_e32 v62, 0x2000, v60
	v_add_u32_e32 v63, 0x3000, v60
	s_add_u32 s14, s8, 0x200000
	s_addc_u32 s15, s9, 0
	v_bfe_u32 v64, v76, 16, 1
	v_add3_u32 v76, v76, v64, s6
	global_store_short_d16_hi v60, v76, s[8:9]
	v_bfe_u32 v64, v77, 16, 1
	v_add3_u32 v77, v77, v64, s6
	global_store_short_d16_hi v61, v77, s[8:9]
	v_bfe_u32 v64, v78, 16, 1
	v_add3_u32 v78, v78, v64, s6
	global_store_short_d16_hi v62, v78, s[8:9]
	v_bfe_u32 v64, v79, 16, 1
	v_add3_u32 v79, v79, v64, s6
	global_store_short_d16_hi v63, v79, s[8:9]
	v_bfe_u32 v64, v80, 16, 1
	v_add3_u32 v80, v80, v64, s6
	global_store_short_d16_hi v60, v80, s[8:9] offset:32
	v_bfe_u32 v64, v81, 16, 1
	v_add3_u32 v81, v81, v64, s6
	global_store_short_d16_hi v61, v81, s[8:9] offset:32
	v_bfe_u32 v64, v82, 16, 1
	v_add3_u32 v82, v82, v64, s6
	global_store_short_d16_hi v62, v82, s[8:9] offset:32
	v_bfe_u32 v64, v83, 16, 1
	v_add3_u32 v83, v83, v64, s6
	global_store_short_d16_hi v63, v83, s[8:9] offset:32
	v_bfe_u32 v64, v84, 16, 1
	v_add3_u32 v84, v84, v64, s6
	global_store_short_d16_hi v60, v84, s[8:9] offset:64
	v_bfe_u32 v64, v85, 16, 1
	v_add3_u32 v85, v85, v64, s6
	global_store_short_d16_hi v61, v85, s[8:9] offset:64
	v_bfe_u32 v64, v86, 16, 1
	v_add3_u32 v86, v86, v64, s6
	global_store_short_d16_hi v62, v86, s[8:9] offset:64
	v_bfe_u32 v64, v87, 16, 1
	v_add3_u32 v87, v87, v64, s6
	global_store_short_d16_hi v63, v87, s[8:9] offset:64
	v_bfe_u32 v64, v88, 16, 1
	v_add3_u32 v88, v88, v64, s6
	global_store_short_d16_hi v60, v88, s[8:9] offset:96
	v_bfe_u32 v64, v89, 16, 1
	v_add3_u32 v89, v89, v64, s6
	global_store_short_d16_hi v61, v89, s[8:9] offset:96
	v_bfe_u32 v64, v90, 16, 1
	v_add3_u32 v90, v90, v64, s6
	global_store_short_d16_hi v62, v90, s[8:9] offset:96
	v_bfe_u32 v64, v91, 16, 1
	v_add3_u32 v91, v91, v64, s6
	global_store_short_d16_hi v63, v91, s[8:9] offset:96
	v_xor_b32_e32 v92, 0x80000000, v92
	v_bfe_u32 v64, v92, 16, 1
	v_add3_u32 v92, v92, v64, s6
	global_store_short_d16_hi v60, v92, s[14:15]
	v_xor_b32_e32 v93, 0x80000000, v93
	v_bfe_u32 v64, v93, 16, 1
	v_add3_u32 v93, v93, v64, s6
	global_store_short_d16_hi v61, v93, s[14:15]
	v_xor_b32_e32 v94, 0x80000000, v94
	v_bfe_u32 v64, v94, 16, 1
	v_add3_u32 v94, v94, v64, s6
	global_store_short_d16_hi v62, v94, s[14:15]
	v_xor_b32_e32 v95, 0x80000000, v95
	v_bfe_u32 v64, v95, 16, 1
	v_add3_u32 v95, v95, v64, s6
	global_store_short_d16_hi v63, v95, s[14:15]
	v_xor_b32_e32 v96, 0x80000000, v96
	v_bfe_u32 v64, v96, 16, 1
	v_add3_u32 v96, v96, v64, s6
	global_store_short_d16_hi v60, v96, s[14:15] offset:32
	v_xor_b32_e32 v97, 0x80000000, v97
	v_bfe_u32 v64, v97, 16, 1
	v_add3_u32 v97, v97, v64, s6
	global_store_short_d16_hi v61, v97, s[14:15] offset:32
	v_xor_b32_e32 v98, 0x80000000, v98
	v_bfe_u32 v64, v98, 16, 1
	v_add3_u32 v98, v98, v64, s6
	global_store_short_d16_hi v62, v98, s[14:15] offset:32
	v_xor_b32_e32 v99, 0x80000000, v99
	v_bfe_u32 v64, v99, 16, 1
	v_add3_u32 v99, v99, v64, s6
	global_store_short_d16_hi v63, v99, s[14:15] offset:32
	v_xor_b32_e32 v100, 0x80000000, v100
	v_bfe_u32 v64, v100, 16, 1
	v_add3_u32 v100, v100, v64, s6
	global_store_short_d16_hi v60, v100, s[14:15] offset:64
	v_xor_b32_e32 v101, 0x80000000, v101
	v_bfe_u32 v64, v101, 16, 1
	v_add3_u32 v101, v101, v64, s6
	global_store_short_d16_hi v61, v101, s[14:15] offset:64
	v_xor_b32_e32 v102, 0x80000000, v102
	v_bfe_u32 v64, v102, 16, 1
	v_add3_u32 v102, v102, v64, s6
	global_store_short_d16_hi v62, v102, s[14:15] offset:64
	v_xor_b32_e32 v103, 0x80000000, v103
	v_bfe_u32 v64, v103, 16, 1
	v_add3_u32 v103, v103, v64, s6
	global_store_short_d16_hi v63, v103, s[14:15] offset:64
	v_xor_b32_e32 v104, 0x80000000, v104
	v_bfe_u32 v64, v104, 16, 1
	v_add3_u32 v104, v104, v64, s6
	global_store_short_d16_hi v60, v104, s[14:15] offset:96
	v_xor_b32_e32 v105, 0x80000000, v105
	v_bfe_u32 v64, v105, 16, 1
	v_add3_u32 v105, v105, v64, s6
	global_store_short_d16_hi v61, v105, s[14:15] offset:96
	v_xor_b32_e32 v106, 0x80000000, v106
	v_bfe_u32 v64, v106, 16, 1
	v_add3_u32 v106, v106, v64, s6
	global_store_short_d16_hi v62, v106, s[14:15] offset:96
	v_xor_b32_e32 v107, 0x80000000, v107
	v_bfe_u32 v64, v107, 16, 1
	v_add3_u32 v107, v107, v64, s6
	global_store_short_d16_hi v63, v107, s[14:15] offset:96
	s_add_i32 s7, s7, s17
	s_cmpk_gt_i32 s7, 0x7f
	s_barrier
	s_cbranch_scc0 .LBB0_53
